# prep loops (a)+(c): per-thread conv weights and biases loaded once before the loop; three dependent weight-load round trips per item in loop (c) removed
# speedup vs baseline: 1.0250x; 1.0159x over previous
.LBB0_313:
	s_or_b64 exec, exec, s[0:1]
	v_readlane_b32 s2, v251, 16
	v_readlane_b32 s3, v251, 17
	s_waitcnt vmcnt(0) lgkmcnt(0)
	s_barrier
	s_load_dword s0, s[2:3], 0x10
	s_nop 0
	s_load_dword s2, s[2:3], 0x0
	s_waitcnt lgkmcnt(0)
	s_lshr_b32 s0, s0, 16
	s_cmp_lg_u32 s0, 0
	s_cselect_b64 s[0:1], -1, 0
	s_cmp_lg_u64 s[0:1], 0
	v_readlane_b32 s0, v251, 27
	s_addc_u32 s28, s2, 0
	s_lshl_b32 s34, s28, 9
	v_add_u32_e32 v58, s0, v59
	s_mov_b32 s0, 0x110000
	v_cmp_gt_i32_e32 vcc, s0, v58
	s_and_saveexec_b64 s[38:39], vcc
	s_cbranch_execz .LBB0_384
	v_readlane_b32 s0, v253, 24
	s_lshl_b32 s26, s28, 13
	s_mov_b64 s[6:7], 0
	v_lshl_add_u32 v76, v59, 3, s0
	v_mov_b32_e32 v74, v76
	v_mov_b32_e32 v39, v58
	v_and_b32_e32 v116, 0xf8, v76
	v_lshlrev_b32_e32 v116, 2, v116
	v_readlane_b32 s2, v254, 48
	v_readlane_b32 s3, v254, 49
	s_nop 4
	global_load_dwordx4 v[84:87], v116, s[2:3]
	global_load_dwordx4 v[88:91], v116, s[2:3] offset:16
	global_load_dwordx4 v[92:95], v116, s[2:3] offset:1024
	global_load_dwordx4 v[96:99], v116, s[2:3] offset:1040
	global_load_dwordx4 v[108:111], v116, s[2:3] offset:2048
	global_load_dwordx4 v[112:115], v116, s[2:3] offset:2064
	s_waitcnt vmcnt(0)
	s_branch .LBB0_317
.LBB0_315:
	s_or_b64 exec, exec, s[0:1]
	global_load_dwordx4 v[100:103], v[26:27], off offset:512
	global_load_dwordx4 v[104:107], v[26:27], off offset:1536
	v_readlane_b32 s0, v254, 48
	v_mov_b32_e32 v39, v9
	v_readlane_b32 s1, v254, 49
	s_waitcnt vmcnt(3)
	v_lshlrev_b32_e32 v28, 16, v18
	v_and_b32_e32 v29, 0xffff0000, v18
	v_lshl_add_u64 v[32:33], s[0:1], 0, v[38:39]
	s_waitcnt vmcnt(2)
	v_lshlrev_b32_e32 v30, 16, v22
	v_and_b32_e32 v31, 0xffff0000, v22
	v_lshlrev_b32_e32 v60, 16, v19
	v_and_b32_e32 v61, 0xffff0000, v19
	v_lshlrev_b32_e32 v48, 16, v20
	v_and_b32_e32 v49, 0xffff0000, v20
	v_lshlrev_b32_e32 v38, 16, v21
	v_and_b32_e32 v39, 0xffff0000, v21
	v_lshlrev_b32_e32 v18, 16, v4
	v_and_b32_e32 v19, 0xffff0000, v4
	v_lshlrev_b32_e32 v20, 16, v14
	v_and_b32_e32 v21, 0xffff0000, v14
	v_lshlrev_b32_e32 v66, 16, v23
	v_and_b32_e32 v67, 0xffff0000, v23
	v_lshlrev_b32_e32 v52, 16, v24
	v_and_b32_e32 v53, 0xffff0000, v24
	v_lshlrev_b32_e32 v42, 16, v25
	v_and_b32_e32 v43, 0xffff0000, v25
	v_lshlrev_b32_e32 v70, 16, v10
	v_and_b32_e32 v71, 0xffff0000, v10
	v_lshlrev_b32_e32 v62, 16, v11
	v_and_b32_e32 v63, 0xffff0000, v11
	v_lshlrev_b32_e32 v50, 16, v12
	v_and_b32_e32 v51, 0xffff0000, v12
	v_lshlrev_b32_e32 v40, 16, v13
	v_and_b32_e32 v41, 0xffff0000, v13
	v_lshlrev_b32_e32 v64, 16, v5
	v_and_b32_e32 v65, 0xffff0000, v5
	v_lshlrev_b32_e32 v54, 16, v6
	v_and_b32_e32 v55, 0xffff0000, v6
	v_lshlrev_b32_e32 v44, 16, v7
	v_and_b32_e32 v45, 0xffff0000, v7
	v_lshlrev_b32_e32 v68, 16, v15
	v_and_b32_e32 v69, 0xffff0000, v15
	v_lshlrev_b32_e32 v56, 16, v16
	v_and_b32_e32 v57, 0xffff0000, v16
	v_lshlrev_b32_e32 v46, 16, v17
	v_and_b32_e32 v47, 0xffff0000, v17
	s_waitcnt vmcnt(0)
	v_mov_b64_e32 v[10:11], v[100:101]
	v_mov_b64_e32 v[12:13], v[102:103]
	v_mov_b64_e32 v[4:5], v[104:105]
	v_mov_b64_e32 v[6:7], v[106:107]
	v_pk_mul_f32 v[22:23], v[20:21], v[30:31]
	v_mov_b64_e32 v[14:15], v[88:89]
	v_mov_b64_e32 v[16:17], v[90:91]
	v_mov_b64_e32 v[24:25], v[84:85]
	v_mov_b64_e32 v[26:27], v[86:87]
	v_pk_mul_f32 v[34:35], v[18:19], v[28:29]
	v_mov_b64_e32 v[18:19], v[96:97]
	v_mov_b64_e32 v[20:21], v[98:99]
	v_mov_b64_e32 v[28:29], v[92:93]
	v_mov_b64_e32 v[30:31], v[94:95]
	v_lshlrev_b32_e32 v78, 16, v0
	v_and_b32_e32 v79, 0xffff0000, v0
	v_pk_mul_f32 v[70:71], v[70:71], v[78:79]
	v_pk_mul_f32 v[60:61], v[64:65], v[60:61]
	v_ashrrev_i32_e32 v37, 31, v36
	v_add_u32_e32 v74, s26, v74
	s_waitcnt vmcnt(5)
	v_lshlrev_b32_e32 v80, 16, v10
	s_waitcnt vmcnt(4)
	v_lshlrev_b32_e32 v0, 16, v4
	v_and_b32_e32 v81, 0xffff0000, v10
	v_and_b32_e32 v4, 0xffff0000, v4
	v_mul_f32_e32 v10, 0xbfb8aa3b, v0
	s_waitcnt vmcnt(0)
	v_pk_mul_f32 v[22:23], v[22:23], v[28:29]
	v_exp_f32_e32 v82, v10
	v_pk_fma_f32 v[28:29], v[34:35], v[24:25], v[22:23]
	v_mov_b64_e32 v[22:23], v[112:113]
	v_mov_b64_e32 v[24:25], v[114:115]
	s_nop 0
	v_mov_b64_e32 v[32:33], v[108:109]
	v_mov_b64_e32 v[34:35], v[110:111]
	v_mul_f32_e32 v10, 0xbfb8aa3b, v4
	v_exp_f32_e32 v83, v10
	s_waitcnt vmcnt(0)
	v_pk_fma_f32 v[28:29], v[70:71], v[32:33], v[28:29]
	v_pk_add_f32 v[32:33], v[82:83], 1.0 op_sel_hi:[1,0]
	v_pk_mul_f32 v[28:29], v[28:29], v[80:81]
	v_div_scale_f32 v10, s[0:1], v33, v33, v4
	v_rcp_f32_e32 v70, v10
	s_nop 0
	v_fma_f32 v71, -v10, v70, 1.0
	v_fmac_f32_e32 v70, v71, v70
	v_div_scale_f32 v71, vcc, v4, v33, v4
	v_mul_f32_e32 v73, v71, v70
	v_fma_f32 v75, -v10, v73, v71
	v_fmac_f32_e32 v73, v75, v70
	v_fma_f32 v10, -v10, v73, v71
	v_div_fmas_f32 v10, v10, v70, v73
	v_div_fixup_f32 v33, v10, v33, v4
	v_div_scale_f32 v4, s[0:1], v32, v32, v0
	v_rcp_f32_e32 v10, v4
	s_nop 0
	v_fma_f32 v70, -v4, v10, 1.0
	v_fmac_f32_e32 v10, v70, v10
	v_div_scale_f32 v70, vcc, v0, v32, v0
	v_mul_f32_e32 v71, v70, v10
	v_fma_f32 v73, -v4, v71, v70
	v_fmac_f32_e32 v71, v73, v10
	v_fma_f32 v4, -v4, v71, v70
	v_div_fmas_f32 v4, v4, v10, v71
	v_div_fixup_f32 v32, v4, v32, v0
	v_pk_mul_f32 v[28:29], v[28:29], v[32:33]
	v_pk_mul_f32 v[32:33], v[68:69], v[66:67]
	v_lshlrev_b32_e32 v66, 16, v5
	v_and_b32_e32 v67, 0xffff0000, v5
	v_mul_f32_e32 v4, 0xbfb8aa3b, v66
	v_mul_f32_e32 v5, 0xbfb8aa3b, v67
	v_exp_f32_e32 v4, v4
	v_exp_f32_e32 v5, v5
	v_lshlrev_b32_e32 v0, 16, v1
	v_and_b32_e32 v1, 0xffff0000, v1
	v_pk_mul_f32 v[30:31], v[32:33], v[30:31]
	v_pk_mul_f32 v[0:1], v[62:63], v[0:1]
	v_pk_fma_f32 v[26:27], v[60:61], v[26:27], v[30:31]
	v_lshlrev_b32_e32 v10, 16, v11
	v_and_b32_e32 v11, 0xffff0000, v11
	v_pk_fma_f32 v[0:1], v[0:1], v[34:35], v[26:27]
	v_pk_add_f32 v[4:5], v[4:5], 1.0 op_sel_hi:[1,0]
	v_pk_mul_f32 v[0:1], v[0:1], v[10:11]
	v_div_scale_f32 v10, s[0:1], v5, v5, v67
	v_rcp_f32_e32 v11, v10
	v_pk_mul_f32 v[32:33], v[54:55], v[48:49]
	v_fma_f32 v26, -v10, v11, 1.0
	v_fmac_f32_e32 v11, v26, v11
	v_div_scale_f32 v26, vcc, v67, v5, v67
	v_mul_f32_e32 v27, v26, v11
	v_fma_f32 v30, -v10, v27, v26
	v_fmac_f32_e32 v27, v30, v11
	v_fma_f32 v10, -v10, v27, v26
	v_div_fmas_f32 v10, v10, v11, v27
	v_div_fixup_f32 v5, v10, v5, v67
	v_div_scale_f32 v10, s[0:1], v4, v4, v66
	v_rcp_f32_e32 v11, v10
	s_nop 0
	v_fma_f32 v26, -v10, v11, 1.0
	v_fmac_f32_e32 v11, v26, v11
	v_div_scale_f32 v26, vcc, v66, v4, v66
	v_mul_f32_e32 v27, v26, v11
	v_fma_f32 v30, -v10, v27, v26
	v_fmac_f32_e32 v27, v30, v11
	v_fma_f32 v10, -v10, v27, v26
	v_div_fmas_f32 v10, v10, v11, v27
	v_div_fixup_f32 v4, v10, v4, v66
	v_pk_mul_f32 v[0:1], v[4:5], v[0:1]
	v_pk_mul_f32 v[4:5], v[56:57], v[52:53]
	v_lshlrev_b32_e32 v10, 16, v2
	v_and_b32_e32 v11, 0xffff0000, v2
	v_pk_mul_f32 v[4:5], v[4:5], v[18:19]
	v_lshlrev_b32_e32 v2, 16, v6
	v_and_b32_e32 v6, 0xffff0000, v6
	v_pk_fma_f32 v[4:5], v[32:33], v[14:15], v[4:5]
	v_pk_mul_f32 v[10:11], v[50:51], v[10:11]
	v_lshlrev_b32_e32 v26, 16, v12
	v_and_b32_e32 v27, 0xffff0000, v12
	v_mul_f32_e32 v12, 0xbfb8aa3b, v2
	v_pk_fma_f32 v[4:5], v[10:11], v[22:23], v[4:5]
	v_mul_f32_e32 v10, 0xbfb8aa3b, v6
	v_exp_f32_e32 v30, v12
	v_exp_f32_e32 v31, v10
	v_pk_mul_f32 v[4:5], v[4:5], v[26:27]
	v_pk_add_f32 v[10:11], v[30:31], 1.0 op_sel_hi:[1,0]
	s_nop 0
	v_div_scale_f32 v12, s[0:1], v11, v11, v6
	v_rcp_f32_e32 v14, v12
	s_nop 0
	v_fma_f32 v15, -v12, v14, 1.0
	v_fmac_f32_e32 v14, v15, v14
	v_div_scale_f32 v15, vcc, v6, v11, v6
	v_mul_f32_e32 v18, v15, v14
	v_fma_f32 v19, -v12, v18, v15
	v_fmac_f32_e32 v18, v19, v14
	v_fma_f32 v12, -v12, v18, v15
	v_div_fmas_f32 v12, v12, v14, v18
	v_div_fixup_f32 v11, v12, v11, v6
	v_div_scale_f32 v6, s[0:1], v10, v10, v2
	v_rcp_f32_e32 v12, v6
	v_and_b32_e32 v19, 0xffff0000, v7
	v_fma_f32 v14, -v6, v12, 1.0
	v_fmac_f32_e32 v12, v14, v12
	v_div_scale_f32 v14, vcc, v2, v10, v2
	v_mul_f32_e32 v15, v14, v12
	v_fma_f32 v18, -v6, v15, v14
	v_fmac_f32_e32 v15, v18, v12
	v_fma_f32 v6, -v6, v15, v14
	v_div_fmas_f32 v6, v6, v12, v15
	v_lshlrev_b32_e32 v18, 16, v7
	v_div_fixup_f32 v10, v6, v10, v2
	v_mul_f32_e32 v6, 0xbfb8aa3b, v18
	v_mul_f32_e32 v7, 0xbfb8aa3b, v19
	v_exp_f32_e32 v6, v6
	v_exp_f32_e32 v7, v7
	v_pk_mul_f32 v[4:5], v[10:11], v[4:5]
	v_pk_mul_f32 v[10:11], v[46:47], v[42:43]
	v_lshlrev_b32_e32 v2, 16, v3
	v_and_b32_e32 v3, 0xffff0000, v3
	v_pk_mul_f32 v[14:15], v[44:45], v[38:39]
	v_pk_mul_f32 v[10:11], v[10:11], v[20:21]
	v_pk_mul_f32 v[2:3], v[40:41], v[2:3]
	v_pk_fma_f32 v[10:11], v[14:15], v[16:17], v[10:11]
	v_pk_add_f32 v[6:7], v[6:7], 1.0 op_sel_hi:[1,0]
	v_pk_fma_f32 v[2:3], v[2:3], v[24:25], v[10:11]
	v_div_scale_f32 v10, s[0:1], v7, v7, v19
	v_rcp_f32_e32 v11, v10
	v_lshlrev_b32_e32 v12, 16, v13
	v_and_b32_e32 v13, 0xffff0000, v13
	v_pk_mul_f32 v[2:3], v[2:3], v[12:13]
	v_fma_f32 v12, -v10, v11, 1.0
	v_fmac_f32_e32 v11, v12, v11
	v_div_scale_f32 v12, vcc, v19, v7, v19
	v_mul_f32_e32 v13, v12, v11
	v_fma_f32 v14, -v10, v13, v12
	v_fmac_f32_e32 v13, v14, v11
	v_fma_f32 v10, -v10, v13, v12
	v_div_fmas_f32 v10, v10, v11, v13
	v_div_fixup_f32 v7, v10, v7, v19
	v_div_scale_f32 v10, s[0:1], v6, v6, v18
	v_rcp_f32_e32 v11, v10
	v_readlane_b32 s0, v251, 59
	v_readlane_b32 s1, v251, 60
	v_add_u32_e32 v39, s34, v72
	v_fma_f32 v12, -v10, v11, 1.0
	v_fmac_f32_e32 v11, v12, v11
	v_div_scale_f32 v12, vcc, v18, v6, v18
	v_mul_f32_e32 v13, v12, v11
	v_fma_f32 v14, -v10, v13, v12
	v_fmac_f32_e32 v13, v14, v11
	v_fma_f32 v10, -v10, v13, v12
	v_div_fmas_f32 v10, v10, v11, v13
	v_div_fixup_f32 v6, v10, v6, v18
	v_pk_mul_f32 v[6:7], v[6:7], v[2:3]
	v_cvt_pk_bf16_f32 v3, v0, v1
	v_lshlrev_b64 v[0:1], 11, v[36:37]
	v_lshl_add_u64 v[0:1], s[0:1], 0, v[0:1]
	s_mov_b32 s0, 0x10ffff
	v_cmp_lt_i32_e32 vcc, s0, v39
	v_cvt_pk_bf16_f32 v2, v28, v29
	v_cvt_pk_bf16_f32 v4, v4, v5
	v_cvt_pk_bf16_f32 v5, v6, v7
	v_lshl_add_u64 v[0:1], v[0:1], 0, v[8:9]
	s_orn2_b64 s[0:1], vcc, exec
	global_store_dwordx4 v[0:1], v[2:5], off

.LBB0_325:
	s_or_b64 exec, exec, s[0:1]
	global_load_dwordx4 v[100:103], v[26:27], off offset:512
	global_load_dwordx4 v[104:107], v[26:27], off offset:1536
	v_readlane_b32 s0, v254, 48
	s_waitcnt vmcnt(3)
	v_lshlrev_b32_e32 v28, 16, v18
	v_and_b32_e32 v29, 0xffff0000, v18
	s_waitcnt vmcnt(2)
	v_lshlrev_b32_e32 v32, 16, v22
	v_and_b32_e32 v33, 0xffff0000, v22
	v_lshlrev_b32_e32 v62, 16, v19
	v_and_b32_e32 v63, 0xffff0000, v19
	v_lshlrev_b32_e32 v50, 16, v20
	v_and_b32_e32 v51, 0xffff0000, v20
	v_lshlrev_b32_e32 v40, 16, v21
	v_and_b32_e32 v41, 0xffff0000, v21
	v_lshlrev_b32_e32 v18, 16, v4
	v_and_b32_e32 v19, 0xffff0000, v4
	v_lshlrev_b32_e32 v20, 16, v14
	v_and_b32_e32 v21, 0xffff0000, v14
	v_lshlrev_b32_e32 v38, 2, v30
	v_readlane_b32 s1, v254, 49
	v_lshlrev_b32_e32 v68, 16, v23
	v_and_b32_e32 v69, 0xffff0000, v23
	v_lshlrev_b32_e32 v54, 16, v24
	v_and_b32_e32 v55, 0xffff0000, v24
	v_lshlrev_b32_e32 v44, 16, v25
	v_and_b32_e32 v45, 0xffff0000, v25
	v_lshlrev_b32_e32 v72, 16, v10
	v_and_b32_e32 v73, 0xffff0000, v10
	v_lshlrev_b32_e32 v64, 16, v11
	v_and_b32_e32 v65, 0xffff0000, v11
	v_lshlrev_b32_e32 v52, 16, v12
	v_and_b32_e32 v53, 0xffff0000, v12
	v_lshlrev_b32_e32 v42, 16, v13
	v_and_b32_e32 v43, 0xffff0000, v13
	v_lshlrev_b32_e32 v66, 16, v5
	v_and_b32_e32 v67, 0xffff0000, v5
	v_lshlrev_b32_e32 v56, 16, v6
	v_and_b32_e32 v57, 0xffff0000, v6
	v_lshlrev_b32_e32 v46, 16, v7
	v_and_b32_e32 v47, 0xffff0000, v7
	v_lshlrev_b32_e32 v70, 16, v15
	v_and_b32_e32 v71, 0xffff0000, v15
	v_lshlrev_b32_e32 v60, 16, v16
	v_and_b32_e32 v61, 0xffff0000, v16
	v_lshlrev_b32_e32 v48, 16, v17
	v_and_b32_e32 v49, 0xffff0000, v17
	s_waitcnt vmcnt(0)
	v_mov_b64_e32 v[10:11], v[100:101]
	v_mov_b64_e32 v[12:13], v[102:103]
	v_mov_b64_e32 v[4:5], v[104:105]
	v_mov_b64_e32 v[6:7], v[106:107]
	v_pk_mul_f32 v[22:23], v[20:21], v[32:33]
	v_mov_b64_e32 v[14:15], v[88:89]
	v_mov_b64_e32 v[16:17], v[90:91]
	v_mov_b64_e32 v[24:25], v[84:85]
	v_mov_b64_e32 v[26:27], v[86:87]
	v_pk_mul_f32 v[32:33], v[18:19], v[28:29]
	v_mov_b64_e32 v[18:19], v[96:97]
	v_mov_b64_e32 v[20:21], v[98:99]
	v_mov_b64_e32 v[28:29], v[92:93]
	v_mov_b64_e32 v[30:31], v[94:95]
	v_lshlrev_b32_e32 v78, 16, v0
	v_and_b32_e32 v79, 0xffff0000, v0
	v_pk_mul_f32 v[72:73], v[72:73], v[78:79]
	v_pk_mul_f32 v[62:63], v[66:67], v[62:63]
	v_ashrrev_i32_e32 v37, 31, v36
	s_waitcnt vmcnt(5)
	v_lshlrev_b32_e32 v80, 16, v10
	s_waitcnt vmcnt(4)
	v_lshlrev_b32_e32 v0, 16, v4
	v_and_b32_e32 v81, 0xffff0000, v10
	v_and_b32_e32 v4, 0xffff0000, v4
	v_mul_f32_e32 v10, 0xbfb8aa3b, v0
	s_waitcnt vmcnt(0)
	v_pk_mul_f32 v[22:23], v[22:23], v[28:29]
	v_exp_f32_e32 v82, v10
	v_pk_fma_f32 v[28:29], v[32:33], v[24:25], v[22:23]
	v_mov_b64_e32 v[22:23], v[112:113]
	v_mov_b64_e32 v[24:25], v[114:115]
	v_mov_b64_e32 v[32:33], v[108:109]
	v_mov_b64_e32 v[34:35], v[110:111]
	v_mul_f32_e32 v10, 0xbfb8aa3b, v4
	v_exp_f32_e32 v83, v10
	s_waitcnt vmcnt(0)
	v_pk_fma_f32 v[28:29], v[72:73], v[32:33], v[28:29]
	v_pk_add_f32 v[32:33], v[82:83], 1.0 op_sel_hi:[1,0]
	v_pk_mul_f32 v[28:29], v[28:29], v[80:81]
	v_div_scale_f32 v10, s[0:1], v33, v33, v4
	v_rcp_f32_e32 v72, v10
	s_nop 0
	v_fma_f32 v73, -v10, v72, 1.0
	v_fmac_f32_e32 v72, v73, v72
	v_div_scale_f32 v73, vcc, v4, v33, v4
	v_mul_f32_e32 v75, v73, v72
	v_fma_f32 v77, -v10, v75, v73
	v_fmac_f32_e32 v75, v77, v72
	v_fma_f32 v10, -v10, v75, v73
	v_div_fmas_f32 v10, v10, v72, v75
	v_div_fixup_f32 v33, v10, v33, v4
	v_div_scale_f32 v4, s[0:1], v32, v32, v0
	v_rcp_f32_e32 v10, v4
	s_nop 0
	v_fma_f32 v72, -v4, v10, 1.0
	v_fmac_f32_e32 v10, v72, v10
	v_div_scale_f32 v72, vcc, v0, v32, v0
	v_mul_f32_e32 v73, v72, v10
	v_fma_f32 v75, -v4, v73, v72
	v_fmac_f32_e32 v73, v75, v10
	v_fma_f32 v4, -v4, v73, v72
	v_div_fmas_f32 v4, v4, v10, v73
	v_div_fixup_f32 v32, v4, v32, v0
	v_pk_mul_f32 v[28:29], v[28:29], v[32:33]
	v_pk_mul_f32 v[32:33], v[70:71], v[68:69]
	v_lshlrev_b32_e32 v68, 16, v5
	v_and_b32_e32 v69, 0xffff0000, v5
	v_mul_f32_e32 v4, 0xbfb8aa3b, v68
	v_mul_f32_e32 v5, 0xbfb8aa3b, v69
	v_exp_f32_e32 v4, v4
	v_exp_f32_e32 v5, v5
	v_lshlrev_b32_e32 v0, 16, v1
	v_and_b32_e32 v1, 0xffff0000, v1
	v_pk_mul_f32 v[30:31], v[32:33], v[30:31]
	v_pk_mul_f32 v[0:1], v[64:65], v[0:1]
	v_pk_fma_f32 v[26:27], v[62:63], v[26:27], v[30:31]
	v_lshlrev_b32_e32 v10, 16, v11
	v_and_b32_e32 v11, 0xffff0000, v11
	v_pk_fma_f32 v[0:1], v[0:1], v[34:35], v[26:27]
	v_pk_add_f32 v[4:5], v[4:5], 1.0 op_sel_hi:[1,0]
	v_pk_mul_f32 v[0:1], v[0:1], v[10:11]
	v_div_scale_f32 v10, s[0:1], v5, v5, v69
	v_rcp_f32_e32 v11, v10
	v_pk_mul_f32 v[32:33], v[56:57], v[50:51]
	v_add_u32_e32 v72, s34, v39
	v_fma_f32 v26, -v10, v11, 1.0
	v_fmac_f32_e32 v11, v26, v11
	v_div_scale_f32 v26, vcc, v69, v5, v69
	v_mul_f32_e32 v27, v26, v11
	v_fma_f32 v30, -v10, v27, v26
	v_fmac_f32_e32 v27, v30, v11
	v_fma_f32 v10, -v10, v27, v26
	v_div_fmas_f32 v10, v10, v11, v27
	v_div_fixup_f32 v5, v10, v5, v69
	v_div_scale_f32 v10, s[0:1], v4, v4, v68
	v_rcp_f32_e32 v11, v10
	s_nop 0
	v_fma_f32 v26, -v10, v11, 1.0
	v_fmac_f32_e32 v11, v26, v11
	v_div_scale_f32 v26, vcc, v68, v4, v68
	v_mul_f32_e32 v27, v26, v11
	v_fma_f32 v30, -v10, v27, v26
	v_fmac_f32_e32 v27, v30, v11
	v_fma_f32 v10, -v10, v27, v26
	v_div_fmas_f32 v10, v10, v11, v27
	v_div_fixup_f32 v4, v10, v4, v68
	v_pk_mul_f32 v[0:1], v[4:5], v[0:1]
	v_pk_mul_f32 v[4:5], v[60:61], v[54:55]
	v_lshlrev_b32_e32 v10, 16, v2
	v_and_b32_e32 v11, 0xffff0000, v2
	v_pk_mul_f32 v[4:5], v[4:5], v[18:19]
	v_lshlrev_b32_e32 v2, 16, v6
	v_and_b32_e32 v6, 0xffff0000, v6
	v_pk_fma_f32 v[4:5], v[32:33], v[14:15], v[4:5]
	v_pk_mul_f32 v[10:11], v[52:53], v[10:11]
	v_lshlrev_b32_e32 v26, 16, v12
	v_and_b32_e32 v27, 0xffff0000, v12
	v_mul_f32_e32 v12, 0xbfb8aa3b, v2
	v_pk_fma_f32 v[4:5], v[10:11], v[22:23], v[4:5]
	v_mul_f32_e32 v10, 0xbfb8aa3b, v6
	v_exp_f32_e32 v30, v12
	v_exp_f32_e32 v31, v10
	v_pk_mul_f32 v[4:5], v[4:5], v[26:27]
	v_pk_add_f32 v[10:11], v[30:31], 1.0 op_sel_hi:[1,0]
	s_nop 0
	v_div_scale_f32 v12, s[0:1], v11, v11, v6
	v_rcp_f32_e32 v14, v12
	s_nop 0
	v_fma_f32 v15, -v12, v14, 1.0
	v_fmac_f32_e32 v14, v15, v14
	v_div_scale_f32 v15, vcc, v6, v11, v6
	v_mul_f32_e32 v18, v15, v14
	v_fma_f32 v19, -v12, v18, v15
	v_fmac_f32_e32 v18, v19, v14
	v_fma_f32 v12, -v12, v18, v15
	v_div_fmas_f32 v12, v12, v14, v18
	v_div_fixup_f32 v11, v12, v11, v6
	v_div_scale_f32 v6, s[0:1], v10, v10, v2
	v_rcp_f32_e32 v12, v6
	v_and_b32_e32 v19, 0xffff0000, v7
	v_fma_f32 v14, -v6, v12, 1.0
	v_fmac_f32_e32 v12, v14, v12
	v_div_scale_f32 v14, vcc, v2, v10, v2
	v_mul_f32_e32 v15, v14, v12
	v_fma_f32 v18, -v6, v15, v14
	v_fmac_f32_e32 v15, v18, v12
	v_fma_f32 v6, -v6, v15, v14
	v_div_fmas_f32 v6, v6, v12, v15
	v_lshlrev_b32_e32 v18, 16, v7
	v_div_fixup_f32 v10, v6, v10, v2
	v_mul_f32_e32 v6, 0xbfb8aa3b, v18
	v_mul_f32_e32 v7, 0xbfb8aa3b, v19
	v_exp_f32_e32 v6, v6
	v_exp_f32_e32 v7, v7
	v_pk_mul_f32 v[4:5], v[10:11], v[4:5]
	v_pk_mul_f32 v[10:11], v[48:49], v[44:45]
	v_lshlrev_b32_e32 v2, 16, v3
	v_and_b32_e32 v3, 0xffff0000, v3
	v_pk_mul_f32 v[14:15], v[46:47], v[40:41]
	v_pk_mul_f32 v[10:11], v[10:11], v[20:21]
	v_pk_mul_f32 v[2:3], v[42:43], v[2:3]
	v_pk_fma_f32 v[10:11], v[14:15], v[16:17], v[10:11]
	v_pk_add_f32 v[6:7], v[6:7], 1.0 op_sel_hi:[1,0]
	v_pk_fma_f32 v[2:3], v[2:3], v[24:25], v[10:11]
	v_div_scale_f32 v10, s[0:1], v7, v7, v19
	v_rcp_f32_e32 v11, v10
	v_lshlrev_b32_e32 v12, 16, v13
	v_and_b32_e32 v13, 0xffff0000, v13
	v_pk_mul_f32 v[2:3], v[2:3], v[12:13]
	v_fma_f32 v12, -v10, v11, 1.0
	v_fmac_f32_e32 v11, v12, v11
	v_div_scale_f32 v12, vcc, v19, v7, v19
	v_mul_f32_e32 v13, v12, v11
	v_fma_f32 v14, -v10, v13, v12
	v_fmac_f32_e32 v13, v14, v11
	v_fma_f32 v10, -v10, v13, v12
	v_div_fmas_f32 v10, v10, v11, v13
	v_div_fixup_f32 v7, v10, v7, v19
	v_div_scale_f32 v10, s[0:1], v6, v6, v18
	v_rcp_f32_e32 v11, v10
	v_readlane_b32 s0, v251, 59
	v_readlane_b32 s1, v251, 60
	v_cvt_pk_bf16_f32 v4, v4, v5
	v_fma_f32 v12, -v10, v11, 1.0
	v_fmac_f32_e32 v11, v12, v11
	v_div_scale_f32 v12, vcc, v18, v6, v18
	v_mul_f32_e32 v13, v12, v11
	v_fma_f32 v14, -v10, v13, v12
	v_fmac_f32_e32 v13, v14, v11
	v_fma_f32 v10, -v10, v13, v12
	v_div_fmas_f32 v10, v10, v11, v13
	v_div_fixup_f32 v6, v10, v6, v18
	v_pk_mul_f32 v[6:7], v[6:7], v[2:3]
	v_cvt_pk_bf16_f32 v3, v0, v1
	v_lshlrev_b64 v[0:1], 11, v[36:37]
	v_lshl_add_u64 v[0:1], s[0:1], 0, v[0:1]
	s_mov_b32 s0, 0x110000
	v_cvt_pk_bf16_f32 v2, v28, v29
	v_cvt_pk_bf16_f32 v5, v6, v7
	v_lshl_add_u64 v[0:1], v[0:1], 0, v[8:9]
	v_cmp_gt_i32_e32 vcc, s0, v72
	s_mov_b64 s[0:1], -1
	global_store_dwordx4 v[0:1], v[2:5], off
	s_and_saveexec_b64 s[18:19], vcc
	s_cbranch_execz .LBB0_316
	v_ashrrev_i32_e32 v36, 5, v72
	s_mov_b32 s0, 0x8000
	v_cmp_gt_i32_e32 vcc, s0, v36
	v_mov_b64_e32 v[2:3], s[70:71]
	v_mad_i64_i32 v[2:3], s[2:3], v36, s77, v[2:3]
	v_cndmask_b32_e32 v0, v222, v223, vcc
	v_and_b32_e32 v1, v0, v36
	v_mov_b32_e32 v10, 0
	v_cmp_ne_u32_e64 s[0:1], 0, v1
	v_lshl_add_u64 v[26:27], v[2:3], 0, v[8:9]
	v_mov_b32_e32 v4, 0
	v_mov_b32_e32 v5, 0
	v_mov_b32_e32 v6, 0
	v_mov_b32_e32 v7, 0
	s_and_saveexec_b64 s[4:5], s[0:1]
	s_cbranch_execz .LBB0_328
	v_add_co_u32_e32 v2, vcc, 0xfffff000, v26
	s_nop 1
	v_addc_co_u32_e32 v3, vcc, -1, v27, vcc
	global_load_dwordx4 v[4:7], v[2:3], off offset:-3072

.LBB0_360:
	s_or_b64 exec, exec, s[0:1]
	v_readlane_b32 s0, v253, 25
	s_mov_b64 s[40:41], 0
	v_mov_b32_e32 v78, v58
	v_lshl_add_u32 v77, v59, 4, s0
	v_and_b32_e32 v116, 0x1c0, v77
	v_and_b32_e32 v117, 24, v76
	v_add_lshl_u32 v116, v116, v117, 2
	v_readlane_b32 s8, v254, 50
	v_readlane_b32 s9, v254, 51
	v_readlane_b32 s12, v254, 52
	v_readlane_b32 s13, v254, 53
	s_nop 0
	s_add_u32 s10, s8, 0x1000
	s_addc_u32 s11, s9, 0
	s_nop 4
	global_load_dwordx4 v[84:87], v116, s[8:9] offset:1024
	global_load_dwordx4 v[88:91], v116, s[8:9] offset:1040
	global_load_dwordx4 v[92:95], v116, s[8:9] offset:1152
	global_load_dwordx4 v[96:99], v116, s[8:9] offset:1168
	global_load_dwordx4 v[100:103], v116, s[10:11]
	global_load_dwordx4 v[104:107], v116, s[10:11] offset:16
	global_load_dwordx4 v[108:111], v116, s[10:11] offset:128
	global_load_dwordx4 v[112:115], v116, s[10:11] offset:144
	global_load_dwordx4 v[120:123], v116, s[10:11] offset:3072
	global_load_dwordx4 v[124:127], v116, s[10:11] offset:3088
	global_load_dwordx4 v[130:133], v116, s[10:11] offset:3200
	global_load_dwordx4 v[164:167], v116, s[10:11] offset:3216
	global_load_dwordx4 v[168:171], v116, s[12:13] offset:1024
	global_load_dwordx4 v[172:175], v116, s[12:13] offset:1040
	global_load_dwordx4 v[176:179], v116, s[12:13] offset:1152
	global_load_dwordx4 v[180:183], v116, s[12:13] offset:1168
	s_waitcnt vmcnt(0)
	s_branch .LBB0_363

.LBB0_367:
	s_or_b64 exec, exec, s[18:19]
	v_add_u32_e32 v69, v5, v79
	v_readlane_b32 s18, v254, 50
	v_lshlrev_b32_e32 v8, 2, v69
	v_readlane_b32 s19, v254, 51
	s_mov_b64 s[2:3], 0x400
	v_mov_b32_e32 v75, v9
	v_lshl_add_u64 v[62:63], s[18:19], 0, v[8:9]
	v_lshl_add_u64 v[70:71], v[62:63], 0, s[2:3]
	s_mov_b64 s[2:3], 0x1c00
	v_lshl_add_u64 v[72:73], v[62:63], 0, s[2:3]
	v_add_co_u32_e32 v2, vcc, 0x1000, v62
	v_readlane_b32 s2, v254, 52
	s_nop 0
	v_addc_co_u32_e32 v3, vcc, 0, v63, vcc
	v_readlane_b32 s3, v254, 53
	v_mov_b64_e32 v[26:27], v[104:105]
	v_mov_b64_e32 v[28:29], v[106:107]
	v_mov_b64_e32 v[42:43], v[100:101]
	v_mov_b64_e32 v[44:45], v[102:103]
	v_mov_b64_e32 v[46:47], v[120:121]
	v_mov_b64_e32 v[48:49], v[122:123]
	v_mov_b64_e32 v[50:51], v[84:85]
	v_mov_b64_e32 v[52:53], v[86:87]
	v_mov_b64_e32 v[30:31], v[124:125]
	v_mov_b64_e32 v[32:33], v[126:127]
	v_mov_b64_e32 v[34:35], v[172:173]
	v_mov_b64_e32 v[36:37], v[174:175]
	v_mov_b64_e32 v[38:39], v[88:89]
	v_mov_b64_e32 v[40:41], v[90:91]
	v_mov_b64_e32 v[54:55], v[168:169]
	v_mov_b64_e32 v[56:57], v[170:171]
	v_or_b32_e32 v2, 32, v4
	v_lshlrev_b32_e32 v74, 1, v2
	v_lshl_add_u64 v[60:61], v[0:1], 0, v[74:75]
	v_mov_b32_e32 v4, 0
	v_mov_b32_e32 v0, 0
	v_mov_b32_e32 v1, 0
	v_mov_b32_e32 v2, 0
	v_mov_b32_e32 v3, 0
	s_and_saveexec_b64 s[18:19], s[0:1]
	s_cbranch_execz .LBB0_369
	v_add_co_u32_e32 v0, vcc, 0xfffff000, v60
	s_nop 1
	v_addc_co_u32_e32 v1, vcc, -1, v61, vcc
	global_load_dwordx4 v[0:3], v[0:1], off offset:-3072

.LBB0_371:
	s_or_b64 exec, exec, s[0:1]
	s_waitcnt vmcnt(3)
	v_lshlrev_b32_e32 v64, 16, v22
	v_and_b32_e32 v65, 0xffff0000, v22
	v_lshlrev_b32_e32 v66, 16, v18
	v_and_b32_e32 v67, 0xffff0000, v18
	s_waitcnt vmcnt(3)
	v_pk_mul_f32 v[42:43], v[42:43], v[64:65]
	v_lshlrev_b32_e32 v82, 16, v14
	v_and_b32_e32 v83, 0xffff0000, v14
	s_waitcnt vmcnt(3)
	v_pk_fma_f32 v[42:43], v[50:51], v[66:67], v[42:43]
	v_readlane_b32 s0, v254, 52
	v_pk_fma_f32 v[42:43], v[46:47], v[82:83], v[42:43]
	v_readlane_b32 s1, v254, 53
	s_waitcnt vmcnt(1)
	v_pk_add_f32 v[42:43], v[54:55], v[42:43]
	v_lshl_add_u64 v[60:61], s[0:1], 0, v[8:9]
	v_mul_f32_e32 v8, 0xbfb8aa3b, v42
	v_exp_f32_e32 v46, v8
	v_mul_f32_e32 v8, 0xbfb8aa3b, v43
	v_exp_f32_e32 v47, v8
	s_nop 0
	v_pk_add_f32 v[46:47], v[46:47], 1.0 op_sel_hi:[1,0]
	s_nop 0
	v_div_scale_f32 v8, s[0:1], v47, v47, v43
	v_rcp_f32_e32 v14, v8
	s_nop 0
	v_fma_f32 v18, -v8, v14, 1.0
	v_fmac_f32_e32 v14, v18, v14
	v_div_scale_f32 v18, vcc, v43, v47, v43
	v_mul_f32_e32 v22, v18, v14
	v_fma_f32 v50, -v8, v22, v18
	v_fmac_f32_e32 v22, v50, v14
	v_fma_f32 v8, -v8, v22, v18
	v_div_fmas_f32 v8, v8, v14, v22
	v_div_fixup_f32 v47, v8, v47, v43
	v_div_scale_f32 v8, s[0:1], v46, v46, v42
	v_rcp_f32_e32 v14, v8
	s_nop 0
	v_fma_f32 v18, -v8, v14, 1.0
	v_fmac_f32_e32 v14, v18, v14
	v_div_scale_f32 v18, vcc, v42, v46, v42
	v_mul_f32_e32 v22, v18, v14
	v_fma_f32 v43, -v8, v22, v18
	v_fmac_f32_e32 v22, v43, v14
	v_fma_f32 v8, -v8, v22, v18
	v_div_fmas_f32 v8, v8, v14, v22
	v_lshlrev_b32_e32 v22, 16, v23
	v_and_b32_e32 v23, 0xffff0000, v23
	v_lshlrev_b32_e32 v18, 16, v19
	v_and_b32_e32 v19, 0xffff0000, v19
	v_pk_mul_f32 v[22:23], v[44:45], v[22:23]
	v_lshlrev_b32_e32 v14, 16, v15
	v_and_b32_e32 v15, 0xffff0000, v15
	v_pk_fma_f32 v[18:19], v[52:53], v[18:19], v[22:23]
	v_div_fixup_f32 v46, v8, v46, v42
	v_pk_fma_f32 v[14:15], v[48:49], v[14:15], v[18:19]
	s_waitcnt vmcnt(0)
	v_lshlrev_b32_e32 v52, 16, v7
	v_pk_add_f32 v[14:15], v[56:57], v[14:15]
	s_nop 0
	v_mul_f32_e32 v8, 0xbfb8aa3b, v14
	v_exp_f32_e32 v18, v8
	v_mul_f32_e32 v8, 0xbfb8aa3b, v15
	v_exp_f32_e32 v19, v8
	s_nop 0
	v_pk_add_f32 v[18:19], v[18:19], 1.0 op_sel_hi:[1,0]
	s_nop 0
	v_div_scale_f32 v8, s[0:1], v19, v19, v15
	v_rcp_f32_e32 v22, v8
	s_nop 0
	v_fma_f32 v23, -v8, v22, 1.0
	v_fmac_f32_e32 v22, v23, v22
	v_div_scale_f32 v23, vcc, v15, v19, v15
	v_mul_f32_e32 v42, v23, v22
	v_fma_f32 v43, -v8, v42, v23
	v_fmac_f32_e32 v42, v43, v22
	v_fma_f32 v8, -v8, v42, v23
	v_div_fmas_f32 v8, v8, v22, v42
	v_div_fixup_f32 v45, v8, v19, v15
	v_div_scale_f32 v8, s[0:1], v18, v18, v14
	v_rcp_f32_e32 v15, v8
	s_nop 0
	v_fma_f32 v19, -v8, v15, 1.0
	v_fmac_f32_e32 v15, v19, v15
	v_div_scale_f32 v19, vcc, v14, v18, v14
	v_mul_f32_e32 v22, v19, v15
	v_fma_f32 v23, -v8, v22, v19
	v_fmac_f32_e32 v22, v23, v15
	v_fma_f32 v8, -v8, v22, v19
	v_div_fmas_f32 v8, v8, v15, v22
	v_div_fixup_f32 v44, v8, v18, v14
	v_lshlrev_b32_e32 v14, 16, v24
	v_and_b32_e32 v15, 0xffff0000, v24
	v_lshlrev_b32_e32 v18, 16, v20
	v_and_b32_e32 v19, 0xffff0000, v20
	v_pk_mul_f32 v[14:15], v[26:27], v[14:15]
	v_lshlrev_b32_e32 v22, 16, v16
	v_and_b32_e32 v23, 0xffff0000, v16
	v_pk_fma_f32 v[14:15], v[38:39], v[18:19], v[14:15]
	v_lshlrev_b32_e32 v24, 16, v0
	v_pk_fma_f32 v[14:15], v[30:31], v[22:23], v[14:15]
	s_nop 0
	v_pk_add_f32 v[14:15], v[34:35], v[14:15]
	s_nop 0
	v_mul_f32_e32 v8, 0xbfb8aa3b, v14
	v_exp_f32_e32 v18, v8
	v_mul_f32_e32 v8, 0xbfb8aa3b, v15
	v_exp_f32_e32 v19, v8
	s_nop 0
	v_pk_add_f32 v[18:19], v[18:19], 1.0 op_sel_hi:[1,0]
	s_nop 0
	v_div_scale_f32 v8, s[0:1], v19, v19, v15
	v_rcp_f32_e32 v16, v8
	s_nop 0
	v_fma_f32 v20, -v8, v16, 1.0
	v_fmac_f32_e32 v16, v20, v16
	v_div_scale_f32 v20, vcc, v15, v19, v15
	v_mul_f32_e32 v22, v20, v16
	v_fma_f32 v23, -v8, v22, v20
	v_fmac_f32_e32 v22, v23, v16
	v_fma_f32 v8, -v8, v22, v20
	v_div_fmas_f32 v8, v8, v16, v22
	v_div_fixup_f32 v49, v8, v19, v15
	v_div_scale_f32 v8, s[0:1], v18, v18, v14
	v_rcp_f32_e32 v15, v8
	v_lshlrev_b32_e32 v22, 16, v10
	v_and_b32_e32 v23, 0xffff0000, v10
	v_fma_f32 v16, -v8, v15, 1.0
	v_fmac_f32_e32 v15, v16, v15
	v_div_scale_f32 v16, vcc, v14, v18, v14
	v_mul_f32_e32 v19, v16, v15
	v_fma_f32 v20, -v8, v19, v16
	v_fmac_f32_e32 v19, v20, v15
	v_fma_f32 v8, -v8, v19, v16
	v_div_fmas_f32 v8, v8, v15, v19
	v_div_fixup_f32 v48, v8, v18, v14
	v_lshlrev_b32_e32 v14, 16, v25
	v_and_b32_e32 v15, 0xffff0000, v25
	v_lshlrev_b32_e32 v18, 16, v21
	v_and_b32_e32 v19, 0xffff0000, v21
	v_pk_mul_f32 v[14:15], v[28:29], v[14:15]
	v_lshlrev_b32_e32 v16, 16, v17
	v_and_b32_e32 v17, 0xffff0000, v17
	v_pk_fma_f32 v[14:15], v[40:41], v[18:19], v[14:15]
	v_and_b32_e32 v25, 0xffff0000, v0
	v_pk_fma_f32 v[14:15], v[32:33], v[16:17], v[14:15]
	v_lshlrev_b32_e32 v40, 16, v4
	v_pk_add_f32 v[14:15], v[36:37], v[14:15]
	v_and_b32_e32 v41, 0xffff0000, v4
	v_mul_f32_e32 v8, 0xbfb8aa3b, v14
	v_exp_f32_e32 v16, v8
	v_mul_f32_e32 v8, 0xbfb8aa3b, v15
	v_exp_f32_e32 v17, v8
	s_nop 0
	v_pk_add_f32 v[16:17], v[16:17], 1.0 op_sel_hi:[1,0]
	s_nop 0
	v_div_scale_f32 v8, s[0:1], v17, v17, v15
	v_rcp_f32_e32 v18, v8
	s_nop 0
	v_fma_f32 v19, -v8, v18, 1.0
	v_fmac_f32_e32 v18, v19, v18
	v_div_scale_f32 v19, vcc, v15, v17, v15
	v_mul_f32_e32 v20, v19, v18
	v_fma_f32 v21, -v8, v20, v19
	v_fmac_f32_e32 v20, v21, v18
	v_fma_f32 v8, -v8, v20, v19
	v_div_fmas_f32 v8, v8, v18, v20
	v_div_fixup_f32 v51, v8, v17, v15
	v_div_scale_f32 v8, s[0:1], v16, v16, v14
	v_rcp_f32_e32 v15, v8
	s_mov_b64 s[0:1], 0x480
	v_lshl_add_u64 v[66:67], v[62:63], 0, s[0:1]
	s_mov_b64 s[0:1], 0x1c80
	v_fma_f32 v17, -v8, v15, 1.0
	v_fmac_f32_e32 v15, v17, v15
	v_div_scale_f32 v17, vcc, v14, v16, v14
	v_mul_f32_e32 v18, v17, v15
	v_fma_f32 v19, -v8, v18, v17
	v_fmac_f32_e32 v18, v19, v15
	v_fma_f32 v8, -v8, v18, v17
	v_div_fmas_f32 v8, v8, v15, v18
	v_div_fixup_f32 v50, v8, v16, v14
	v_mov_b64_e32 v[14:15], v[96:97]
	v_mov_b64_e32 v[16:17], v[98:99]
	v_mov_b64_e32 v[28:29], v[92:93]
	v_mov_b64_e32 v[30:31], v[94:95]
	v_mov_b64_e32 v[18:19], v[112:113]
	v_mov_b64_e32 v[20:21], v[114:115]
	v_mov_b64_e32 v[32:33], v[108:109]
	v_mov_b64_e32 v[34:35], v[110:111]
	v_lshl_add_u64 v[64:65], v[62:63], 0, s[0:1]
	s_movk_i32 s0, 0x1000
	v_lshlrev_b32_e32 v8, 16, v3
	s_waitcnt vmcnt(0)
	v_pk_mul_f32 v[22:23], v[32:33], v[22:23]
	s_nop 0
	v_pk_fma_f32 v[22:23], v[28:29], v[24:25], v[22:23]
	v_add_co_u32_e32 v24, vcc, s0, v62
	s_nop 1
	v_addc_co_u32_e32 v25, vcc, 0, v63, vcc
	v_mov_b64_e32 v[36:37], v[130:131]
	v_mov_b64_e32 v[38:39], v[132:133]
	v_mov_b64_e32 v[26:27], v[164:165]
	v_mov_b64_e32 v[28:29], v[166:167]
	s_waitcnt vmcnt(0)
	v_pk_fma_f32 v[32:33], v[36:37], v[40:41], v[22:23]
	v_mov_b64_e32 v[22:23], v[180:181]
	v_mov_b64_e32 v[24:25], v[182:183]
	v_mov_b64_e32 v[40:41], v[176:177]
	v_mov_b64_e32 v[42:43], v[178:179]
	s_waitcnt vmcnt(0)
	v_pk_add_f32 v[32:33], v[40:41], v[32:33]
	s_nop 0
	v_mul_f32_e32 v0, 0xbfb8aa3b, v32
	v_exp_f32_e32 v36, v0
	v_mul_f32_e32 v0, 0xbfb8aa3b, v33
	v_exp_f32_e32 v37, v0
	s_nop 0
	v_pk_add_f32 v[36:37], v[36:37], 1.0 op_sel_hi:[1,0]
	s_nop 0
	v_div_scale_f32 v0, s[0:1], v37, v37, v33
	v_rcp_f32_e32 v4, v0
	s_nop 0
	v_fma_f32 v10, -v0, v4, 1.0
	v_fmac_f32_e32 v4, v10, v4
	v_div_scale_f32 v10, vcc, v33, v37, v33
	v_mul_f32_e32 v40, v10, v4
	v_fma_f32 v41, -v0, v40, v10
	v_fmac_f32_e32 v40, v41, v4
	v_fma_f32 v0, -v0, v40, v10
	v_div_fmas_f32 v0, v0, v4, v40
	v_div_fixup_f32 v33, v0, v37, v33
	v_div_scale_f32 v0, s[0:1], v36, v36, v32
	v_rcp_f32_e32 v4, v0
	s_nop 0
	v_fma_f32 v10, -v0, v4, 1.0
	v_fmac_f32_e32 v4, v10, v4
	v_div_scale_f32 v10, vcc, v32, v36, v32
	v_mul_f32_e32 v37, v10, v4
	v_fma_f32 v40, -v0, v37, v10
	v_fmac_f32_e32 v37, v40, v4
	v_fma_f32 v0, -v0, v37, v10
	v_div_fmas_f32 v0, v0, v4, v37
	v_lshlrev_b32_e32 v10, 16, v11
	v_and_b32_e32 v11, 0xffff0000, v11
	v_div_fixup_f32 v32, v0, v36, v32
	v_lshlrev_b32_e32 v0, 16, v1
	v_and_b32_e32 v1, 0xffff0000, v1
	v_pk_mul_f32 v[10:11], v[34:35], v[10:11]
	v_lshlrev_b32_e32 v4, 16, v5
	v_and_b32_e32 v5, 0xffff0000, v5
	v_pk_fma_f32 v[0:1], v[30:31], v[0:1], v[10:11]
	s_nop 0
	v_pk_fma_f32 v[0:1], v[38:39], v[4:5], v[0:1]
	s_nop 0
	v_pk_add_f32 v[0:1], v[42:43], v[0:1]
	s_nop 0
	v_mul_f32_e32 v4, 0xbfb8aa3b, v0
	v_mul_f32_e32 v5, 0xbfb8aa3b, v1
	v_exp_f32_e32 v4, v4
	v_exp_f32_e32 v5, v5
	s_nop 0
	v_pk_add_f32 v[4:5], v[4:5], 1.0 op_sel_hi:[1,0]
	s_nop 0
	v_div_scale_f32 v10, s[0:1], v5, v5, v1
	v_rcp_f32_e32 v11, v10
	s_nop 0
	v_fma_f32 v30, -v10, v11, 1.0
	v_fmac_f32_e32 v11, v30, v11
	v_div_scale_f32 v30, vcc, v1, v5, v1
	v_mul_f32_e32 v31, v30, v11
	v_fma_f32 v34, -v10, v31, v30
	v_fmac_f32_e32 v31, v34, v11
	v_fma_f32 v10, -v10, v31, v30
	v_div_fmas_f32 v10, v10, v11, v31
	v_div_fixup_f32 v1, v10, v5, v1
	v_div_scale_f32 v5, s[0:1], v4, v4, v0
	v_rcp_f32_e32 v10, v5
	s_nop 0
	v_fma_f32 v11, -v5, v10, 1.0
	v_fmac_f32_e32 v10, v11, v10
	v_div_scale_f32 v11, vcc, v0, v4, v0
	v_mul_f32_e32 v30, v11, v10
	v_fma_f32 v31, -v5, v30, v11
	v_fmac_f32_e32 v30, v31, v10
	v_fma_f32 v5, -v5, v30, v11
	v_div_fmas_f32 v5, v5, v10, v30
	v_div_fixup_f32 v0, v5, v4, v0
	v_lshlrev_b32_e32 v4, 16, v12
	v_and_b32_e32 v5, 0xffff0000, v12
	v_lshlrev_b32_e32 v10, 16, v2
	v_and_b32_e32 v11, 0xffff0000, v2
	v_pk_mul_f32 v[4:5], v[18:19], v[4:5]
	v_lshlrev_b32_e32 v30, 16, v6
	v_and_b32_e32 v31, 0xffff0000, v6
	v_pk_fma_f32 v[4:5], v[14:15], v[10:11], v[4:5]
	s_nop 0
	v_pk_fma_f32 v[4:5], v[26:27], v[30:31], v[4:5]
	s_nop 0
	v_pk_add_f32 v[4:5], v[22:23], v[4:5]
	s_nop 0
	v_mul_f32_e32 v2, 0xbfb8aa3b, v4
	v_exp_f32_e32 v10, v2
	v_mul_f32_e32 v2, 0xbfb8aa3b, v5
	v_exp_f32_e32 v11, v2
	s_nop 0
	v_pk_add_f32 v[10:11], v[10:11], 1.0 op_sel_hi:[1,0]
	s_nop 0
	v_div_scale_f32 v2, s[0:1], v11, v11, v5
	v_rcp_f32_e32 v6, v2
	s_nop 0
	v_fma_f32 v12, -v2, v6, 1.0
	v_fmac_f32_e32 v6, v12, v6
	v_div_scale_f32 v12, vcc, v5, v11, v5
	v_mul_f32_e32 v14, v12, v6
	v_fma_f32 v15, -v2, v14, v12
	v_fmac_f32_e32 v14, v15, v6
	v_fma_f32 v2, -v2, v14, v12
	v_div_fmas_f32 v2, v2, v6, v14
	v_div_fixup_f32 v5, v2, v11, v5
	v_div_scale_f32 v2, s[0:1], v10, v10, v4
	v_rcp_f32_e32 v6, v2
	s_nop 0
	v_fma_f32 v11, -v2, v6, 1.0
	v_fmac_f32_e32 v6, v11, v6
	v_div_scale_f32 v11, vcc, v4, v10, v4
	v_mul_f32_e32 v12, v11, v6
	v_fma_f32 v14, -v2, v12, v11
	v_fmac_f32_e32 v12, v14, v6
	v_fma_f32 v2, -v2, v12, v11
	v_div_fmas_f32 v2, v2, v6, v12
	v_div_fixup_f32 v4, v2, v10, v4
	v_mul_f32_e32 v6, v28, v52
	v_and_b32_e32 v11, 0xffff0000, v7
	v_and_b32_e32 v10, 0xffff0000, v3
	v_mov_b32_e32 v28, v17
	v_pk_mul_f32 v[10:11], v[28:29], v[10:11]
	v_mul_f32_e32 v2, v16, v8
	v_lshlrev_b32_e32 v12, 16, v13
	v_and_b32_e32 v13, 0xffff0000, v13
	v_mov_b32_e32 v3, v10
	v_pk_fma_f32 v[2:3], v[20:21], v[12:13], v[2:3]
	v_mov_b32_e32 v7, v11
	v_pk_add_f32 v[2:3], v[2:3], v[6:7]
	s_nop 0
	v_pk_add_f32 v[2:3], v[24:25], v[2:3]
	s_nop 0
	v_mul_f32_e32 v6, 0xbfb8aa3b, v2
	v_mul_f32_e32 v7, 0xbfb8aa3b, v3
	v_exp_f32_e32 v6, v6
	v_exp_f32_e32 v7, v7
	s_nop 0
	v_pk_add_f32 v[6:7], v[6:7], 1.0 op_sel_hi:[1,0]
	s_nop 0
	v_div_scale_f32 v8, s[0:1], v7, v7, v3
	v_rcp_f32_e32 v10, v8
	s_nop 0
	v_fma_f32 v11, -v8, v10, 1.0
	v_fmac_f32_e32 v10, v11, v10
	v_div_scale_f32 v11, vcc, v3, v7, v3
	v_mul_f32_e32 v12, v11, v10
	v_fma_f32 v13, -v8, v12, v11
	v_fmac_f32_e32 v12, v13, v10
	v_fma_f32 v8, -v8, v12, v11
	v_div_fmas_f32 v8, v8, v10, v12
	v_div_fixup_f32 v3, v8, v7, v3
	v_div_scale_f32 v7, s[0:1], v6, v6, v2
	v_rcp_f32_e32 v8, v7
	s_nop 0
	v_fma_f32 v10, -v7, v8, 1.0
	v_fmac_f32_e32 v8, v10, v8
	v_div_scale_f32 v10, vcc, v2, v6, v2
	v_mul_f32_e32 v11, v10, v8
	v_fma_f32 v12, -v7, v11, v10
	v_fmac_f32_e32 v11, v12, v8
	v_fma_f32 v7, -v7, v11, v10
	v_div_fmas_f32 v7, v7, v8, v11
	v_div_fixup_f32 v2, v7, v6, v2
	s_and_saveexec_b64 s[0:1], s[6:7]
	s_cbranch_execz .LBB0_373
	v_and_b32_e32 v6, 4, v78
	v_lshrrev_b32_e32 v7, 6, v80
	v_cmp_eq_u32_e32 vcc, 0, v6
	s_nop 1
	v_cndmask_b32_e32 v6, v80, v7, vcc
	v_lshlrev_b32_e32 v6, 8, v6
	v_and_b32_e32 v6, 0x3f00, v6
	v_lshlrev_b32_e32 v7, 3, v79
	v_add3_u32 v6, 0, v6, v7
	ds_read_b128 v[10:13], v6
	ds_read_b128 v[14:17], v6 offset:16
	ds_read_b128 v[18:21], v6 offset:32
	ds_read_b128 v[22:25], v6 offset:48
	s_waitcnt lgkmcnt(3)
	v_mov_b32_e32 v7, v12
	v_mov_b32_e32 v12, v11
	v_mov_b32_e32 v6, v10
	v_pk_mul_f32 v[10:11], v[32:33], v[12:13]
	s_waitcnt lgkmcnt(0)
	v_mov_b32_e32 v8, v23
	v_pk_fma_f32 v[10:11], v[46:47], v[6:7], v[10:11] neg_lo:[0,0,1] neg_hi:[0,0,1]
	v_pk_mul_f32 v[6:7], v[32:33], v[6:7]
	s_nop 0
	v_pk_fma_f32 v[32:33], v[46:47], v[12:13], v[6:7]
	v_mov_b32_e32 v7, v16
	v_mov_b32_e32 v16, v15
	v_mov_b32_e32 v6, v14
	v_pk_mul_f32 v[12:13], v[0:1], v[16:17]
	v_pk_mul_f32 v[0:1], v[0:1], v[6:7]
	v_pk_fma_f32 v[12:13], v[44:45], v[6:7], v[12:13] neg_lo:[0,0,1] neg_hi:[0,0,1]
	v_mov_b32_e32 v6, v18
	v_mov_b32_e32 v7, v20
	v_mov_b32_e32 v20, v19
	v_pk_mul_f32 v[14:15], v[4:5], v[20:21]
	v_pk_mul_f32 v[4:5], v[4:5], v[6:7]
	v_pk_fma_f32 v[0:1], v[44:45], v[16:17], v[0:1]
	v_pk_fma_f32 v[4:5], v[48:49], v[20:21], v[4:5]
	v_pk_mul_f32 v[16:17], v[2:3], v[8:9]
	v_pk_mul_f32 v[20:21], v[2:3], v[22:23]
	v_mov_b32_e32 v2, v51
	v_pk_fma_f32 v[14:15], v[48:49], v[6:7], v[14:15] neg_lo:[0,0,1] neg_hi:[0,0,1]
	v_pk_mul_f32 v[6:7], v[50:51], v[22:23]
	v_pk_mul_f32 v[18:19], v[50:51], v[8:9]
	v_pk_mul_f32 v[22:23], v[2:3], v[24:25]
	v_mov_b32_e32 v50, v3
	v_mov_b32_e32 v7, v22
	v_mov_b32_e32 v17, v23
	v_pk_mul_f32 v[2:3], v[50:51], v[24:25]
	v_pk_add_f32 v[6:7], v[6:7], v[16:17] neg_lo:[0,1] neg_hi:[0,1]
	v_mov_b32_e32 v19, v3
	v_mov_b32_e32 v21, v2
	v_pk_add_f32 v[2:3], v[18:19], v[20:21]
	v_mov_b64_e32 v[50:51], v[6:7]
	v_mov_b32_e32 v46, v10
	v_mov_b32_e32 v47, v11
	v_mov_b32_e32 v44, v12
	v_mov_b32_e32 v45, v13
	v_mov_b32_e32 v48, v14
	v_mov_b32_e32 v49, v15

.LBB0_378:
	s_or_b64 exec, exec, s[24:25]
	v_mov_b64_e32 v[26:27], v[88:89]
	v_mov_b64_e32 v[28:29], v[90:91]
	v_mov_b64_e32 v[42:43], v[84:85]
	v_mov_b64_e32 v[44:45], v[86:87]
	v_mov_b64_e32 v[30:31], v[104:105]
	v_mov_b64_e32 v[32:33], v[106:107]
	v_mov_b64_e32 v[54:55], v[100:101]
	v_mov_b64_e32 v[56:57], v[102:103]
	v_mov_b64_e32 v[34:35], v[124:125]
	v_mov_b64_e32 v[36:37], v[126:127]
	v_mov_b64_e32 v[46:47], v[120:121]
	v_mov_b64_e32 v[48:49], v[122:123]
	v_mov_b64_e32 v[38:39], v[172:173]
	v_mov_b64_e32 v[40:41], v[174:175]
	v_mov_b64_e32 v[50:51], v[168:169]
	v_mov_b64_e32 v[52:53], v[170:171]
	v_mov_b32_e32 v75, v9
	v_lshl_add_u64 v[68:69], v[0:1], 0, v[74:75]
	v_mov_b32_e32 v4, 0
	v_mov_b32_e32 v0, 0
	v_mov_b32_e32 v1, 0
	v_mov_b32_e32 v2, 0
	v_mov_b32_e32 v3, 0
	s_and_saveexec_b64 s[24:25], s[0:1]
	s_cbranch_execz .LBB0_380
	v_add_co_u32_e32 v0, vcc, 0xfffff000, v68
	s_nop 1
	v_addc_co_u32_e32 v1, vcc, -1, v69, vcc
	global_load_dwordx4 v[0:3], v[0:1], off offset:-3072

.LBB0_382:
	s_or_b64 exec, exec, s[0:1]
	s_waitcnt vmcnt(3)
	v_lshlrev_b32_e32 v68, 16, v22
	v_and_b32_e32 v69, 0xffff0000, v22
	v_lshlrev_b32_e32 v70, 16, v18
	v_and_b32_e32 v71, 0xffff0000, v18
	s_waitcnt vmcnt(3)
	v_pk_mul_f32 v[54:55], v[54:55], v[68:69]
	v_lshlrev_b32_e32 v72, 16, v14
	v_and_b32_e32 v73, 0xffff0000, v14
	v_pk_fma_f32 v[42:43], v[42:43], v[70:71], v[54:55]
	s_waitcnt vmcnt(3)
	v_pk_fma_f32 v[42:43], v[46:47], v[72:73], v[42:43]
	s_waitcnt vmcnt(1)
	v_pk_add_f32 v[42:43], v[50:51], v[42:43]
	s_nop 0
	v_mul_f32_e32 v14, 0xbfb8aa3b, v42
	v_exp_f32_e32 v46, v14
	v_mul_f32_e32 v14, 0xbfb8aa3b, v43
	v_exp_f32_e32 v47, v14
	s_nop 0
	v_pk_add_f32 v[46:47], v[46:47], 1.0 op_sel_hi:[1,0]
	s_nop 0
	v_div_scale_f32 v14, s[0:1], v47, v47, v43
	v_rcp_f32_e32 v18, v14
	s_nop 0
	v_fma_f32 v22, -v14, v18, 1.0
	v_fmac_f32_e32 v18, v22, v18
	v_div_scale_f32 v22, vcc, v43, v47, v43
	v_mul_f32_e32 v50, v22, v18
	v_fma_f32 v51, -v14, v50, v22
	v_fmac_f32_e32 v50, v51, v18
	v_fma_f32 v14, -v14, v50, v22
	v_div_fmas_f32 v14, v14, v18, v50
	v_div_fixup_f32 v47, v14, v47, v43
	v_div_scale_f32 v14, s[0:1], v46, v46, v42
	v_rcp_f32_e32 v18, v14
	s_nop 0
	v_fma_f32 v22, -v14, v18, 1.0
	v_fmac_f32_e32 v18, v22, v18
	v_div_scale_f32 v22, vcc, v42, v46, v42
	v_mul_f32_e32 v43, v22, v18
	v_fma_f32 v50, -v14, v43, v22
	v_fmac_f32_e32 v43, v50, v18
	v_fma_f32 v14, -v14, v43, v22
	v_lshlrev_b32_e32 v22, 16, v23
	v_and_b32_e32 v23, 0xffff0000, v23
	v_div_fmas_f32 v14, v14, v18, v43
	v_lshlrev_b32_e32 v18, 16, v19
	v_and_b32_e32 v19, 0xffff0000, v19
	v_pk_mul_f32 v[22:23], v[56:57], v[22:23]
	v_div_fixup_f32 v46, v14, v46, v42
	v_lshlrev_b32_e32 v14, 16, v15
	v_and_b32_e32 v15, 0xffff0000, v15
	v_pk_fma_f32 v[18:19], v[44:45], v[18:19], v[22:23]
	s_nop 0
	v_pk_fma_f32 v[14:15], v[48:49], v[14:15], v[18:19]
	s_nop 0
	v_pk_add_f32 v[14:15], v[52:53], v[14:15]
	s_waitcnt vmcnt(0)
	v_lshlrev_b32_e32 v53, 16, v7
	v_mul_f32_e32 v18, 0xbfb8aa3b, v14
	v_mul_f32_e32 v19, 0xbfb8aa3b, v15
	v_exp_f32_e32 v18, v18
	v_exp_f32_e32 v19, v19
	v_lshlrev_b32_e32 v52, 16, v3
	v_pk_add_f32 v[18:19], v[18:19], 1.0 op_sel_hi:[1,0]
	s_nop 0
	v_div_scale_f32 v22, s[0:1], v19, v19, v15
	v_rcp_f32_e32 v23, v22
	s_nop 0
	v_fma_f32 v42, -v22, v23, 1.0
	v_fmac_f32_e32 v23, v42, v23
	v_div_scale_f32 v42, vcc, v15, v19, v15
	v_mul_f32_e32 v43, v42, v23
	v_fma_f32 v44, -v22, v43, v42
	v_fmac_f32_e32 v43, v44, v23
	v_fma_f32 v22, -v22, v43, v42
	v_div_fmas_f32 v22, v22, v23, v43
	v_div_fixup_f32 v45, v22, v19, v15
	v_div_scale_f32 v15, s[0:1], v18, v18, v14
	v_rcp_f32_e32 v19, v15
	s_nop 0
	v_fma_f32 v22, -v15, v19, 1.0
	v_fmac_f32_e32 v19, v22, v19
	v_div_scale_f32 v22, vcc, v14, v18, v14
	v_mul_f32_e32 v23, v22, v19
	v_fma_f32 v42, -v15, v23, v22
	v_fmac_f32_e32 v23, v42, v19
	v_fma_f32 v15, -v15, v23, v22
	v_div_fmas_f32 v15, v15, v19, v23
	v_div_fixup_f32 v44, v15, v18, v14
	v_lshlrev_b32_e32 v14, 16, v24
	v_and_b32_e32 v15, 0xffff0000, v24
	v_lshlrev_b32_e32 v18, 16, v20
	v_and_b32_e32 v19, 0xffff0000, v20
	v_pk_mul_f32 v[14:15], v[30:31], v[14:15]
	v_lshlrev_b32_e32 v22, 16, v16
	v_and_b32_e32 v23, 0xffff0000, v16
	v_pk_fma_f32 v[14:15], v[26:27], v[18:19], v[14:15]
	v_lshlrev_b32_e32 v26, 16, v4
	v_pk_fma_f32 v[14:15], v[34:35], v[22:23], v[14:15]
	v_and_b32_e32 v27, 0xffff0000, v4
	v_pk_add_f32 v[14:15], v[38:39], v[14:15]
	s_nop 0
	v_mul_f32_e32 v16, 0xbfb8aa3b, v14
	v_exp_f32_e32 v18, v16
	v_mul_f32_e32 v16, 0xbfb8aa3b, v15
	v_exp_f32_e32 v19, v16
	s_nop 0
	v_pk_add_f32 v[18:19], v[18:19], 1.0 op_sel_hi:[1,0]
	s_nop 0
	v_div_scale_f32 v16, s[0:1], v19, v19, v15
	v_rcp_f32_e32 v20, v16
	s_nop 0
	v_fma_f32 v22, -v16, v20, 1.0
	v_fmac_f32_e32 v20, v22, v20
	v_div_scale_f32 v22, vcc, v15, v19, v15
	v_mul_f32_e32 v23, v22, v20
	v_fma_f32 v24, -v16, v23, v22
	v_fmac_f32_e32 v23, v24, v20
	v_fma_f32 v16, -v16, v23, v22
	v_div_fmas_f32 v16, v16, v20, v23
	v_div_fixup_f32 v49, v16, v19, v15
	v_div_scale_f32 v15, s[0:1], v18, v18, v14
	v_rcp_f32_e32 v16, v15
	v_and_b32_e32 v23, 0xffff0000, v10
	v_lshlrev_b32_e32 v24, 16, v0
	v_fma_f32 v19, -v15, v16, 1.0
	v_fmac_f32_e32 v16, v19, v16
	v_div_scale_f32 v19, vcc, v14, v18, v14
	v_mul_f32_e32 v20, v19, v16
	v_fma_f32 v22, -v15, v20, v19
	v_fmac_f32_e32 v20, v22, v16
	v_fma_f32 v15, -v15, v20, v19
	v_div_fmas_f32 v15, v15, v16, v20
	v_div_fixup_f32 v48, v15, v18, v14
	v_lshlrev_b32_e32 v14, 16, v25
	v_and_b32_e32 v15, 0xffff0000, v25
	v_lshlrev_b32_e32 v18, 16, v21
	v_and_b32_e32 v19, 0xffff0000, v21
	v_pk_mul_f32 v[14:15], v[32:33], v[14:15]
	v_lshlrev_b32_e32 v16, 16, v17
	v_and_b32_e32 v17, 0xffff0000, v17
	v_pk_fma_f32 v[14:15], v[28:29], v[18:19], v[14:15]
	v_and_b32_e32 v25, 0xffff0000, v0
	v_pk_fma_f32 v[14:15], v[36:37], v[16:17], v[14:15]
	s_nop 0
	v_pk_add_f32 v[14:15], v[40:41], v[14:15]
	s_nop 0
	v_mul_f32_e32 v16, 0xbfb8aa3b, v14
	v_mul_f32_e32 v17, 0xbfb8aa3b, v15
	v_exp_f32_e32 v16, v16
	v_exp_f32_e32 v17, v17
	s_nop 0
	v_pk_add_f32 v[16:17], v[16:17], 1.0 op_sel_hi:[1,0]
	s_nop 0
	v_div_scale_f32 v18, s[0:1], v17, v17, v15
	v_rcp_f32_e32 v19, v18
	s_nop 0
	v_fma_f32 v20, -v18, v19, 1.0
	v_fmac_f32_e32 v19, v20, v19
	v_div_scale_f32 v20, vcc, v15, v17, v15
	v_mul_f32_e32 v21, v20, v19
	v_fma_f32 v22, -v18, v21, v20
	v_fmac_f32_e32 v21, v22, v19
	v_fma_f32 v18, -v18, v21, v20
	v_div_fmas_f32 v18, v18, v19, v21
	v_div_fixup_f32 v51, v18, v17, v15
	v_div_scale_f32 v15, s[0:1], v16, v16, v14
	v_rcp_f32_e32 v17, v15
	v_lshlrev_b32_e32 v22, 16, v10
	v_fma_f32 v18, -v15, v17, 1.0
	v_fmac_f32_e32 v17, v18, v17
	v_div_scale_f32 v18, vcc, v14, v16, v14
	v_mul_f32_e32 v19, v18, v17
	v_fma_f32 v20, -v15, v19, v18
	v_fmac_f32_e32 v19, v20, v17
	v_fma_f32 v15, -v15, v19, v18
	v_div_fmas_f32 v15, v15, v17, v19
	v_div_fixup_f32 v50, v15, v16, v14
	v_mov_b64_e32 v[18:19], v[96:97]
	v_mov_b64_e32 v[20:21], v[98:99]
	v_mov_b64_e32 v[28:29], v[92:93]
	v_mov_b64_e32 v[30:31], v[94:95]
	v_mov_b64_e32 v[14:15], v[112:113]
	v_mov_b64_e32 v[16:17], v[114:115]
	v_mov_b64_e32 v[32:33], v[108:109]
	v_mov_b64_e32 v[34:35], v[110:111]
	s_waitcnt vmcnt(0)
	v_pk_mul_f32 v[22:23], v[32:33], v[22:23]
	s_nop 0
	v_pk_fma_f32 v[28:29], v[28:29], v[24:25], v[22:23]
	v_mov_b64_e32 v[22:23], v[164:165]
	v_mov_b64_e32 v[24:25], v[166:167]
	v_mov_b64_e32 v[36:37], v[130:131]
	v_mov_b64_e32 v[38:39], v[132:133]
	s_waitcnt vmcnt(0)
	v_pk_fma_f32 v[32:33], v[36:37], v[26:27], v[28:29]
	v_mov_b64_e32 v[26:27], v[180:181]
	v_mov_b64_e32 v[28:29], v[182:183]
	v_mov_b64_e32 v[40:41], v[176:177]
	v_mov_b64_e32 v[42:43], v[178:179]
	s_waitcnt vmcnt(0)
	v_pk_add_f32 v[32:33], v[40:41], v[32:33]
	s_nop 0
	v_mul_f32_e32 v0, 0xbfb8aa3b, v32
	v_exp_f32_e32 v36, v0
	v_mul_f32_e32 v0, 0xbfb8aa3b, v33
	v_exp_f32_e32 v37, v0
	s_nop 0
	v_pk_add_f32 v[36:37], v[36:37], 1.0 op_sel_hi:[1,0]
	s_nop 0
	v_div_scale_f32 v0, s[0:1], v37, v37, v33
	v_rcp_f32_e32 v4, v0
	s_nop 0
	v_fma_f32 v10, -v0, v4, 1.0
	v_fmac_f32_e32 v4, v10, v4
	v_div_scale_f32 v10, vcc, v33, v37, v33
	v_mul_f32_e32 v40, v10, v4
	v_fma_f32 v41, -v0, v40, v10
	v_fmac_f32_e32 v40, v41, v4
	v_fma_f32 v0, -v0, v40, v10
	v_div_fmas_f32 v0, v0, v4, v40
	v_div_fixup_f32 v33, v0, v37, v33
	v_div_scale_f32 v0, s[0:1], v36, v36, v32
	v_rcp_f32_e32 v4, v0
	s_nop 0
	v_fma_f32 v10, -v0, v4, 1.0
	v_fmac_f32_e32 v4, v10, v4
	v_div_scale_f32 v10, vcc, v32, v36, v32
	v_mul_f32_e32 v37, v10, v4
	v_fma_f32 v40, -v0, v37, v10
	v_fmac_f32_e32 v37, v40, v4
	v_fma_f32 v0, -v0, v37, v10
	v_div_fmas_f32 v0, v0, v4, v37
	v_lshlrev_b32_e32 v10, 16, v11
	v_and_b32_e32 v11, 0xffff0000, v11
	v_div_fixup_f32 v32, v0, v36, v32
	v_lshlrev_b32_e32 v0, 16, v1
	v_and_b32_e32 v1, 0xffff0000, v1
	v_pk_mul_f32 v[10:11], v[34:35], v[10:11]
	v_lshlrev_b32_e32 v4, 16, v5
	v_and_b32_e32 v5, 0xffff0000, v5
	v_pk_fma_f32 v[0:1], v[30:31], v[0:1], v[10:11]
	s_nop 0
	v_pk_fma_f32 v[0:1], v[38:39], v[4:5], v[0:1]
	s_nop 0
	v_pk_add_f32 v[0:1], v[42:43], v[0:1]
	s_nop 0
	v_mul_f32_e32 v4, 0xbfb8aa3b, v0
	v_mul_f32_e32 v5, 0xbfb8aa3b, v1
	v_exp_f32_e32 v4, v4
	v_exp_f32_e32 v5, v5
	s_nop 0
	v_pk_add_f32 v[4:5], v[4:5], 1.0 op_sel_hi:[1,0]
	s_nop 0
	v_div_scale_f32 v10, s[0:1], v5, v5, v1
	v_rcp_f32_e32 v11, v10
	s_nop 0
	v_fma_f32 v30, -v10, v11, 1.0
	v_fmac_f32_e32 v11, v30, v11
	v_div_scale_f32 v30, vcc, v1, v5, v1
	v_mul_f32_e32 v31, v30, v11
	v_fma_f32 v34, -v10, v31, v30
	v_fmac_f32_e32 v31, v34, v11
	v_fma_f32 v10, -v10, v31, v30
	v_div_fmas_f32 v10, v10, v11, v31
	v_div_fixup_f32 v1, v10, v5, v1
	v_div_scale_f32 v5, s[0:1], v4, v4, v0
	v_rcp_f32_e32 v10, v5
	s_nop 0
	v_fma_f32 v11, -v5, v10, 1.0
	v_fmac_f32_e32 v10, v11, v10
	v_div_scale_f32 v11, vcc, v0, v4, v0
	v_mul_f32_e32 v30, v11, v10
	v_fma_f32 v31, -v5, v30, v11
	v_fmac_f32_e32 v30, v31, v10
	v_fma_f32 v5, -v5, v30, v11
	v_div_fmas_f32 v5, v5, v10, v30
	v_div_fixup_f32 v0, v5, v4, v0
	v_lshlrev_b32_e32 v4, 16, v12
	v_and_b32_e32 v5, 0xffff0000, v12
	v_lshlrev_b32_e32 v10, 16, v2
	v_and_b32_e32 v11, 0xffff0000, v2
	v_pk_mul_f32 v[4:5], v[14:15], v[4:5]
	v_lshlrev_b32_e32 v30, 16, v6
	v_and_b32_e32 v31, 0xffff0000, v6
	v_pk_fma_f32 v[4:5], v[18:19], v[10:11], v[4:5]
	s_nop 0
	v_pk_fma_f32 v[4:5], v[22:23], v[30:31], v[4:5]
	s_nop 0
	v_pk_add_f32 v[4:5], v[26:27], v[4:5]
	s_nop 0
	v_mul_f32_e32 v2, 0xbfb8aa3b, v4
	v_exp_f32_e32 v10, v2
	v_mul_f32_e32 v2, 0xbfb8aa3b, v5
	v_exp_f32_e32 v11, v2
	s_nop 0
	v_pk_add_f32 v[10:11], v[10:11], 1.0 op_sel_hi:[1,0]
	s_nop 0
	v_div_scale_f32 v2, s[0:1], v11, v11, v5
	v_rcp_f32_e32 v6, v2
	s_nop 0
	v_fma_f32 v12, -v2, v6, 1.0
	v_fmac_f32_e32 v6, v12, v6
	v_div_scale_f32 v12, vcc, v5, v11, v5
	v_mul_f32_e32 v14, v12, v6
	v_fma_f32 v15, -v2, v14, v12
	v_fmac_f32_e32 v14, v15, v6
	v_fma_f32 v2, -v2, v14, v12
	v_div_fmas_f32 v2, v2, v6, v14
	v_div_fixup_f32 v5, v2, v11, v5
	v_div_scale_f32 v2, s[0:1], v10, v10, v4
	v_rcp_f32_e32 v6, v2
	s_nop 0
	v_fma_f32 v11, -v2, v6, 1.0
	v_fmac_f32_e32 v6, v11, v6
	v_div_scale_f32 v11, vcc, v4, v10, v4
	v_mul_f32_e32 v12, v11, v6
	v_fma_f32 v14, -v2, v12, v11
	v_fmac_f32_e32 v12, v14, v6
	v_fma_f32 v2, -v2, v12, v11
	v_div_fmas_f32 v2, v2, v6, v12
	v_div_fixup_f32 v4, v2, v10, v4
	v_mul_f32_e32 v6, v24, v53
	v_and_b32_e32 v11, 0xffff0000, v7
	v_and_b32_e32 v10, 0xffff0000, v3
	v_mov_b32_e32 v24, v21
	v_pk_mul_f32 v[10:11], v[24:25], v[10:11]
	v_mul_f32_e32 v2, v20, v52
	v_lshlrev_b32_e32 v12, 16, v13
	v_and_b32_e32 v13, 0xffff0000, v13
	v_mov_b32_e32 v3, v10
	v_pk_fma_f32 v[2:3], v[16:17], v[12:13], v[2:3]
	v_mov_b32_e32 v7, v11
	v_pk_add_f32 v[2:3], v[2:3], v[6:7]
	s_nop 0
	v_pk_add_f32 v[2:3], v[28:29], v[2:3]
	s_nop 0
	v_mul_f32_e32 v6, 0xbfb8aa3b, v2
	v_mul_f32_e32 v7, 0xbfb8aa3b, v3
	v_exp_f32_e32 v6, v6
	v_exp_f32_e32 v7, v7
	s_nop 0
	v_pk_add_f32 v[6:7], v[6:7], 1.0 op_sel_hi:[1,0]
	s_nop 0
	v_div_scale_f32 v10, s[0:1], v7, v7, v3
	v_rcp_f32_e32 v11, v10
	s_nop 0
	v_fma_f32 v12, -v10, v11, 1.0
	v_fmac_f32_e32 v11, v12, v11
	v_div_scale_f32 v12, vcc, v3, v7, v3
	v_mul_f32_e32 v13, v12, v11
	v_fma_f32 v14, -v10, v13, v12
	v_fmac_f32_e32 v13, v14, v11
	v_fma_f32 v10, -v10, v13, v12
	v_div_fmas_f32 v10, v10, v11, v13
	v_div_fixup_f32 v3, v10, v7, v3
	v_div_scale_f32 v7, s[0:1], v6, v6, v2
	v_rcp_f32_e32 v10, v7
	s_nop 0
	v_fma_f32 v11, -v7, v10, 1.0
	v_fmac_f32_e32 v10, v11, v10
	v_div_scale_f32 v11, vcc, v2, v6, v2
	v_mul_f32_e32 v12, v11, v10
	v_fma_f32 v13, -v7, v12, v11
	v_fmac_f32_e32 v12, v13, v10
	v_fma_f32 v7, -v7, v12, v11
	v_div_fmas_f32 v7, v7, v10, v12
	v_div_fixup_f32 v2, v7, v6, v2
	s_and_saveexec_b64 s[0:1], s[6:7]
	s_cbranch_execz .LBB0_361
	v_and_b32_e32 v6, 4, v78
	v_lshrrev_b32_e32 v7, 6, v81
	v_cmp_eq_u32_e32 vcc, 0, v6
	s_nop 1
	v_cndmask_b32_e32 v6, v81, v7, vcc
	v_lshlrev_b32_e32 v6, 8, v6
	v_and_b32_e32 v6, 0x3f00, v6
	v_lshlrev_b32_e32 v7, 3, v79
	v_add3_u32 v6, 0, v6, v7
	ds_read_b128 v[10:13], v6
	ds_read_b128 v[14:17], v6 offset:16
	ds_read_b128 v[18:21], v6 offset:32
	ds_read_b128 v[22:25], v6 offset:48
	s_waitcnt lgkmcnt(3)
	v_mov_b32_e32 v7, v12
	v_mov_b32_e32 v12, v11
	v_mov_b32_e32 v6, v10
	v_pk_mul_f32 v[10:11], v[32:33], v[12:13]
	s_nop 0
	v_pk_fma_f32 v[10:11], v[46:47], v[6:7], v[10:11] neg_lo:[0,0,1] neg_hi:[0,0,1]
	v_pk_mul_f32 v[6:7], v[32:33], v[6:7]
	s_nop 0
	v_pk_fma_f32 v[32:33], v[46:47], v[12:13], v[6:7]
	s_waitcnt lgkmcnt(2)
	v_mov_b32_e32 v7, v16
	v_mov_b32_e32 v16, v15
	v_mov_b32_e32 v6, v14
	v_pk_mul_f32 v[12:13], v[0:1], v[16:17]
	v_pk_mul_f32 v[0:1], v[0:1], v[6:7]
	v_pk_fma_f32 v[12:13], v[44:45], v[6:7], v[12:13] neg_lo:[0,0,1] neg_hi:[0,0,1]
	s_waitcnt lgkmcnt(1)
	v_mov_b32_e32 v6, v18
	v_mov_b32_e32 v7, v20
	v_mov_b32_e32 v20, v19
	v_pk_fma_f32 v[0:1], v[44:45], v[16:17], v[0:1]
	v_pk_mul_f32 v[14:15], v[4:5], v[20:21]
	v_pk_mul_f32 v[4:5], v[4:5], v[6:7]
	s_waitcnt lgkmcnt(0)
	v_mov_b32_e32 v16, v23
	v_pk_fma_f32 v[4:5], v[48:49], v[20:21], v[4:5]
	v_pk_mul_f32 v[18:19], v[2:3], v[16:17]
	v_pk_mul_f32 v[20:21], v[2:3], v[22:23]
	v_mov_b32_e32 v2, v51
	v_pk_fma_f32 v[14:15], v[48:49], v[6:7], v[14:15] neg_lo:[0,0,1] neg_hi:[0,0,1]
	v_pk_mul_f32 v[6:7], v[50:51], v[22:23]
	v_pk_mul_f32 v[16:17], v[50:51], v[16:17]
	v_pk_mul_f32 v[22:23], v[2:3], v[24:25]
	v_mov_b32_e32 v50, v3
	v_mov_b32_e32 v7, v22
	v_mov_b32_e32 v19, v23
	v_pk_mul_f32 v[2:3], v[50:51], v[24:25]
	v_pk_add_f32 v[6:7], v[6:7], v[18:19] neg_lo:[0,1] neg_hi:[0,1]
	v_mov_b32_e32 v17, v3
	v_mov_b32_e32 v21, v2
	v_pk_add_f32 v[2:3], v[16:17], v[20:21]
	v_mov_b64_e32 v[50:51], v[6:7]
	v_mov_b32_e32 v46, v10
	v_mov_b32_e32 v47, v11
	v_mov_b32_e32 v44, v12
	v_mov_b32_e32 v45, v13
	v_mov_b32_e32 v48, v14
	v_mov_b32_e32 v49, v15
	s_branch .LBB0_361
